# cross-unit fragment prefetch P1/P8: next unit's first K-step ds_reads issued in previous epilogue tail into dead fragment VGPRs, stacked on v66
# baseline (speedup 1.0000x reference)
.LBB0_193:
	s_mov_b64 s[38:39], 0x80
	v_lshl_add_u64 v[10:11], v[2:3], 0, s[38:39]
	s_add_i32 m0, s11, 0x18000
	s_mov_b64 s[40:41], 0x20080
	s_waitcnt vmcnt(2)
	s_barrier
	global_load_lds_dwordx4 v[10:11], off
	v_lshl_add_u64 v[10:11], v[2:3], 0, s[40:41]
	s_add_i32 m0, s11, 0x1a000
	s_add_i32 s57, s11, 0x8000
	global_load_lds_dwordx4 v[10:11], off
	v_lshl_add_u64 v[10:11], v[4:5], 0, s[38:39]
	s_mov_b32 m0, s57
	s_add_i32 s58, s11, 0xa000
	global_load_lds_dwordx4 v[10:11], off
	v_lshl_add_u64 v[4:5], v[4:5], 0, s[40:41]
	s_mov_b32 m0, s58
	s_mov_b64 s[42:43], 0x40080
	global_load_lds_dwordx4 v[4:5], off
	v_lshl_add_u64 v[4:5], v[2:3], 0, s[42:43]
	s_add_i32 m0, s11, 0x1c000
	s_mov_b64 s[44:45], 0x60080
	global_load_lds_dwordx4 v[4:5], off
	v_lshl_add_u64 v[2:3], v[2:3], 0, s[44:45]
	s_add_i32 m0, s11, 0x1e000
	v_bfe_u32 v143, v0, 4, 2
	global_load_lds_dwordx4 v[2:3], off
	s_sext_i32_i16 s60, s0
	v_lshlrev_b32_e32 v2, 4, v143
	v_lshlrev_b32_e32 v3, 6, v0
	s_movk_i32 s0, 0x3c0
	v_lshlrev_b32_e32 v5, 2, v1
	v_and_or_b32 v3, v3, s0, v2
	v_lshl_or_b32 v2, v1, 6, v2
	s_lshl_b32 s0, s2, 13
	v_and_b32_e32 v5, 32, v5
	v_bitop3_b32 v2, v2, s0, v5 bitop3:0xde
	s_lshl_b32 s0, s3, 5
	v_lshlrev_b32_e32 v4, 2, v0
	s_and_b32 s61, s0, 0x60
	v_and_b32_e32 v4, 32, v4
	s_lshl_b32 s59, s2, 6
	s_lshl_b32 s0, s61, 7
	v_bitop3_b32 v144, s0, v3, v4 bitop3:0xf6
	s_mov_b32 s0, 0x18000
	s_cmpk_lt_u32 s1, 0x100
	v_lshlrev_b32_e32 v3, 8, v0
	v_lshlrev_b32_e32 v4, 11, v6
	s_waitcnt vmcnt(6)
	s_cselect_b64 s[62:63], -1, 0
	s_lshl_b32 s1, s2, 10
	v_and_or_b32 v3, v3, s0, v4
	v_add_u32_e32 v4, v7, v8
	s_add_i32 s76, s1, 0
	v_and_b32_e32 v4, 0xe0, v4
	s_add_i32 s96, 0, 0x10000
	s_add_i32 s97, 0, 0x14000
	s_mov_b32 s53, 0
	s_add_i32 s76, s76, 0x22000
	v_or3_b32 v134, v3, v4, v9
	v_mov_b32_e32 v135, v133
	v_mov_b64_e32 v[136:137], 0x5d8
	v_mov_b64_e32 v[138:139], 0x5d7
	v_add_u32_e32 v145, s96, v144
	v_add_u32_e32 v146, s97, v144
	v_add_u32_e32 v147, 0, v2
	s_mov_b64 s[64:65], 0x100
	s_mov_b64 s[66:67], 0x20100
	s_mov_b64 s[72:73], 0x40100
	s_mov_b64 s[74:75], 0x60100
	s_mov_b64 s[78:79], 0x180
	s_mov_b64 s[82:83], 0x20180
	s_mov_b64 s[84:85], 0x40180
	s_mov_b64 s[86:87], 0x60180
	v_mov_b32_e32 v148, 0x358637bd
	s_movk_i32 s50, 0x1600
	s_barrier
	ds_read_b128 v[216:219], v145
	ds_read_b128 v[220:223], v145 offset:1024
	ds_read_b128 v[228:231], v145 offset:2048
	ds_read_b128 v[232:235], v145 offset:3072
	ds_read_b128 v[236:239], v146
	ds_read_b128 v[240:243], v146 offset:1024
	ds_read_b128 v[244:247], v146 offset:2048
	ds_read_b128 v[248:251], v146 offset:3072
	ds_read_b128 v[180:183], v147
	ds_read_b128 v[188:191], v147 offset:1024
	ds_read_b128 v[192:195], v147 offset:2048
	ds_read_b128 v[196:199], v147 offset:3072
	ds_read_b128 v[200:203], v147 offset:4096
	ds_read_b128 v[204:207], v147 offset:5120
	ds_read_b128 v[208:211], v147 offset:6144
	ds_read_b128 v[212:215], v147 offset:7168
	s_branch .LBB0_195

.LBB0_200:
	s_add_u32 s46, s6, 0x200
	s_addc_u32 s47, s7, 0
	s_ashr_i32 s91, s90, 31
	s_lshl_b64 s[2:3], s[90:91], 19
	v_readlane_b32 s8, v254, 62
	v_readlane_b32 s9, v254, 63
	s_add_u32 s94, s8, s2
	s_addc_u32 s95, s9, s3
	s_and_b64 s[2:3], s[0:1], exec
	s_cselect_b32 s48, s95, s25
	s_cselect_b32 s49, s94, s24
	s_ashr_i32 s89, s88, 31
	s_lshl_b64 s[2:3], s[88:89], 19
	s_add_u32 s92, s68, s2
	s_addc_u32 s93, s69, s3
	s_and_b64 s[2:3], s[0:1], exec
	s_cselect_b32 s89, s93, s7
	s_cselect_b32 s91, s92, s6
	v_lshl_add_u64 v[140:141], s[24:25], 0, v[130:131]
	s_add_i32 vcc_lo, s11, 0xc000
	v_lshl_add_u64 v[66:67], v[140:141], 0, s[42:43]
	s_mov_b32 m0, vcc_lo
	s_add_i32 vcc_hi, s11, 0xe000
	global_load_lds_dwordx4 v[66:67], off
	v_lshl_add_u64 v[66:67], v[140:141], 0, s[44:45]
	s_mov_b32 m0, vcc_hi
	s_nop 0
	global_load_lds_dwordx4 v[66:67], off
	s_waitcnt vmcnt(8)
	s_waitcnt lgkmcnt(0)
	s_waitcnt lgkmcnt(0)
	v_mfma_f32_16x16x32_bf16 v[86:89], v[228:231], v[200:203], 0
	v_mfma_f32_16x16x32_bf16 v[90:93], v[232:235], v[204:207], v[86:89]
	s_barrier
	s_setprio 1
	v_mfma_f32_16x16x32_bf16 v[86:89], v[216:219], v[208:211], 0
	v_mfma_f32_16x16x32_bf16 v[66:69], v[216:219], v[180:183], 0
	v_mfma_f32_16x16x32_bf16 v[70:73], v[228:231], v[180:183], 0
	v_mfma_f32_16x16x32_bf16 v[74:77], v[216:219], v[192:195], 0
	v_mfma_f32_16x16x32_bf16 v[78:81], v[228:231], v[192:195], 0
	v_mfma_f32_16x16x32_bf16 v[82:85], v[216:219], v[200:203], 0
	v_mfma_f32_16x16x32_bf16 v[94:97], v[220:223], v[212:215], v[86:89]
	v_mfma_f32_16x16x32_bf16 v[86:89], v[228:231], v[208:211], 0
	v_mfma_f32_16x16x32_bf16 v[66:69], v[220:223], v[188:191], v[66:69]
	v_mfma_f32_16x16x32_bf16 v[70:73], v[232:235], v[188:191], v[70:73]
	v_mfma_f32_16x16x32_bf16 v[74:77], v[220:223], v[196:199], v[74:77]
	v_mfma_f32_16x16x32_bf16 v[78:81], v[232:235], v[196:199], v[78:81]
	v_mfma_f32_16x16x32_bf16 v[82:85], v[220:223], v[204:207], v[82:85]
	v_mfma_f32_16x16x32_bf16 v[106:109], v[232:235], v[212:215], v[86:89]
	s_setprio 0
	s_setprio 1
	v_mfma_f32_16x16x32_bf16 v[86:89], v[236:239], v[180:183], 0
	v_mfma_f32_16x16x32_bf16 v[34:37], v[244:247], v[180:183], 0
	v_mfma_f32_16x16x32_bf16 v[110:113], v[240:243], v[188:191], v[86:89]
	v_mfma_f32_16x16x32_bf16 v[34:37], v[248:251], v[188:191], v[34:37]
	v_mfma_f32_16x16x32_bf16 v[38:41], v[236:239], v[192:195], 0
	v_mfma_f32_16x16x32_bf16 v[42:45], v[244:247], v[192:195], 0
	v_mfma_f32_16x16x32_bf16 v[38:41], v[240:243], v[196:199], v[38:41]
	v_mfma_f32_16x16x32_bf16 v[42:45], v[248:251], v[196:199], v[42:45]
	v_mfma_f32_16x16x32_bf16 v[46:49], v[236:239], v[200:203], 0
	v_mfma_f32_16x16x32_bf16 v[50:53], v[244:247], v[200:203], 0
	v_mfma_f32_16x16x32_bf16 v[46:49], v[240:243], v[204:207], v[46:49]
	v_mfma_f32_16x16x32_bf16 v[50:53], v[248:251], v[204:207], v[50:53]
	v_mfma_f32_16x16x32_bf16 v[54:57], v[236:239], v[208:211], 0
	v_mfma_f32_16x16x32_bf16 v[58:61], v[244:247], v[208:211], 0
	v_mfma_f32_16x16x32_bf16 v[54:57], v[240:243], v[212:215], v[54:57]
	v_mfma_f32_16x16x32_bf16 v[58:61], v[248:251], v[212:215], v[58:61]
	s_setprio 0
	s_barrier
	v_lshl_add_u64 v[184:185], s[6:7], 0, v[132:133]
	s_add_i32 s8, s96, s51
	v_lshl_add_u64 v[150:151], v[184:185], 0, s[64:65]
	s_mov_b32 m0, s8
	s_add_i32 s9, s8, 0x2000
	ds_read_b128 v[62:65], v147 offset:16384
	ds_read_b128 v[86:89], v147 offset:17408
	ds_read_b128 v[98:101], v147 offset:18432
	ds_read_b128 v[102:105], v147 offset:19456
	ds_read_b128 v[114:117], v147 offset:20480
	ds_read_b128 v[118:121], v147 offset:21504
	ds_read_b128 v[122:125], v147 offset:22528
	ds_read_b128 v[126:129], v147 offset:23552
	global_load_lds_dwordx4 v[150:151], off
	v_lshl_add_u64 v[150:151], v[184:185], 0, s[66:67]
	s_mov_b32 m0, s9
	s_add_i32 s33, s97, s51
	global_load_lds_dwordx4 v[150:151], off
	v_lshl_add_u64 v[150:151], v[184:185], 0, s[72:73]
	s_mov_b32 m0, s33
	s_add_i32 s2, s33, 0x2000
	global_load_lds_dwordx4 v[150:151], off
	v_lshl_add_u64 v[150:151], v[184:185], 0, s[74:75]
	s_mov_b32 m0, s2
	s_nop 0
	global_load_lds_dwordx4 v[150:151], off
	v_lshl_add_u64 v[150:151], v[140:141], 0, s[64:65]
	s_mov_b32 m0, s11
	s_nop 0
	global_load_lds_dwordx4 v[150:151], off
	v_lshl_add_u64 v[150:151], v[140:141], 0, s[66:67]
	s_mov_b32 m0, s54
	s_nop 0
	global_load_lds_dwordx4 v[150:151], off
	s_waitcnt vmcnt(8)
	s_waitcnt lgkmcnt(0)
	s_waitcnt lgkmcnt(0)
	v_mfma_f32_16x16x32_bf16 v[150:153], v[216:219], v[62:65], 0
	v_mfma_f32_16x16x32_bf16 v[160:163], v[216:219], v[98:101], 0
	s_barrier
	s_setprio 1
	v_mfma_f32_16x16x32_bf16 v[168:171], v[216:219], v[114:117], 0
	v_mfma_f32_16x16x32_bf16 v[2:5], v[216:219], v[122:125], 0
	v_mfma_f32_16x16x32_bf16 v[152:155], v[220:223], v[86:89], v[150:153]
	v_mfma_f32_16x16x32_bf16 v[160:163], v[220:223], v[102:105], v[160:163]
	v_mfma_f32_16x16x32_bf16 v[168:171], v[220:223], v[118:121], v[168:171]
	v_mfma_f32_16x16x32_bf16 v[2:5], v[220:223], v[126:129], v[2:5]
	v_mfma_f32_16x16x32_bf16 v[6:9], v[228:231], v[122:125], 0
	v_mfma_f32_16x16x32_bf16 v[156:159], v[228:231], v[62:65], 0
	v_mfma_f32_16x16x32_bf16 v[164:167], v[228:231], v[98:101], 0
	v_mfma_f32_16x16x32_bf16 v[172:175], v[228:231], v[114:117], 0
	v_mfma_f32_16x16x32_bf16 v[10:13], v[232:235], v[126:129], v[6:9]
	v_mfma_f32_16x16x32_bf16 v[156:159], v[232:235], v[86:89], v[156:159]
	v_mfma_f32_16x16x32_bf16 v[164:167], v[232:235], v[102:105], v[164:167]
	v_mfma_f32_16x16x32_bf16 v[172:175], v[232:235], v[118:121], v[172:175]
	s_setprio 0
	s_setprio 1
	v_mfma_f32_16x16x32_bf16 v[6:9], v[236:239], v[62:65], 0
	v_mfma_f32_16x16x32_bf16 v[14:17], v[240:243], v[86:89], v[6:9]
	v_mfma_f32_16x16x32_bf16 v[6:9], v[244:247], v[62:65], 0
	v_mfma_f32_16x16x32_bf16 v[176:179], v[248:251], v[86:89], v[6:9]
	v_mfma_f32_16x16x32_bf16 v[6:9], v[236:239], v[98:101], 0
	v_mfma_f32_16x16x32_bf16 v[180:183], v[240:243], v[102:105], v[6:9]
	v_mfma_f32_16x16x32_bf16 v[6:9], v[244:247], v[98:101], 0
	v_mfma_f32_16x16x32_bf16 v[188:191], v[248:251], v[102:105], v[6:9]
	v_mfma_f32_16x16x32_bf16 v[6:9], v[236:239], v[114:117], 0
	v_mfma_f32_16x16x32_bf16 v[192:195], v[240:243], v[118:121], v[6:9]
	v_mfma_f32_16x16x32_bf16 v[6:9], v[244:247], v[114:117], 0
	v_mfma_f32_16x16x32_bf16 v[196:199], v[248:251], v[118:121], v[6:9]
	v_mfma_f32_16x16x32_bf16 v[6:9], v[236:239], v[122:125], 0
	v_mfma_f32_16x16x32_bf16 v[200:203], v[240:243], v[126:129], v[6:9]
	v_mfma_f32_16x16x32_bf16 v[6:9], v[244:247], v[122:125], 0
	v_mfma_f32_16x16x32_bf16 v[204:207], v[248:251], v[126:129], v[6:9]
	s_setprio 0
	s_barrier
	s_add_i32 s3, 0, 0x18000
	s_add_i32 s35, 0, 0x1c000
	v_add_u32_e32 v149, s3, v144
	v_add_u32_e32 v150, s35, v144
	s_nop 0
	ds_read_b128 v[6:9], v149
	ds_read_b128 v[26:29], v149 offset:1024
	ds_read_b128 v[30:33], v149 offset:2048
	ds_read_b128 v[208:211], v149 offset:3072
	ds_read_b128 v[212:215], v150
	ds_read_b128 v[216:219], v150 offset:1024
	ds_read_b128 v[220:223], v150 offset:2048
	ds_read_b128 v[224:227], v150 offset:3072
	s_mov_b32 m0, s55
	v_lshl_add_u64 v[62:63], v[140:141], 0, s[72:73]
	ds_read_b128 v[18:21], v147 offset:32768
	ds_read_b128 v[22:25], v147 offset:33792
	ds_read_b128 v[228:231], v147 offset:34816
	ds_read_b128 v[232:235], v147 offset:35840
	ds_read_b128 v[236:239], v147 offset:36864
	ds_read_b128 v[240:243], v147 offset:37888
	ds_read_b128 v[244:247], v147 offset:38912
	ds_read_b128 v[248:251], v147 offset:39936
	global_load_lds_dwordx4 v[62:63], off
	v_lshl_add_u64 v[62:63], v[140:141], 0, s[74:75]
	s_mov_b32 m0, s56
	s_nop 0
	global_load_lds_dwordx4 v[62:63], off
	s_waitcnt vmcnt(8)
	s_waitcnt lgkmcnt(0)
	s_waitcnt lgkmcnt(0)
	v_mfma_f32_16x16x32_bf16 v[62:65], v[6:9], v[18:21], v[66:69]
	v_mfma_f32_16x16x32_bf16 v[118:121], v[26:29], v[22:25], v[62:65]
	s_barrier
	s_setprio 1
	v_mfma_f32_16x16x32_bf16 v[62:65], v[30:33], v[18:21], v[70:73]
	v_mfma_f32_16x16x32_bf16 v[114:117], v[208:211], v[22:25], v[62:65]
	v_mfma_f32_16x16x32_bf16 v[62:65], v[6:9], v[228:231], v[74:77]
	v_mfma_f32_16x16x32_bf16 v[102:105], v[26:29], v[232:235], v[62:65]
	v_mfma_f32_16x16x32_bf16 v[62:65], v[30:33], v[228:231], v[78:81]
	v_mfma_f32_16x16x32_bf16 v[98:101], v[208:211], v[232:235], v[62:65]
	v_mfma_f32_16x16x32_bf16 v[62:65], v[6:9], v[236:239], v[82:85]
	v_mfma_f32_16x16x32_bf16 v[86:89], v[26:29], v[240:243], v[62:65]
	v_mfma_f32_16x16x32_bf16 v[62:65], v[30:33], v[236:239], v[90:93]
	v_mfma_f32_16x16x32_bf16 v[82:85], v[208:211], v[240:243], v[62:65]
	v_mfma_f32_16x16x32_bf16 v[62:65], v[6:9], v[244:247], v[94:97]
	v_mfma_f32_16x16x32_bf16 v[70:73], v[26:29], v[248:251], v[62:65]
	v_mfma_f32_16x16x32_bf16 v[62:65], v[30:33], v[244:247], v[106:109]
	v_mfma_f32_16x16x32_bf16 v[62:65], v[208:211], v[248:251], v[62:65]
	s_setprio 0
	s_setprio 1
	v_mfma_f32_16x16x32_bf16 v[66:69], v[212:215], v[18:21], v[110:113]
	v_mfma_f32_16x16x32_bf16 v[18:21], v[220:223], v[18:21], v[34:37]
	v_mfma_f32_16x16x32_bf16 v[122:125], v[224:227], v[22:25], v[18:21]
	v_mfma_f32_16x16x32_bf16 v[18:21], v[212:215], v[228:231], v[38:41]
	v_mfma_f32_16x16x32_bf16 v[110:113], v[216:219], v[232:235], v[18:21]
	v_mfma_f32_16x16x32_bf16 v[18:21], v[220:223], v[228:231], v[42:45]
	v_mfma_f32_16x16x32_bf16 v[106:109], v[224:227], v[232:235], v[18:21]
	v_mfma_f32_16x16x32_bf16 v[18:21], v[212:215], v[236:239], v[46:49]
	v_mfma_f32_16x16x32_bf16 v[94:97], v[216:219], v[240:243], v[18:21]
	v_mfma_f32_16x16x32_bf16 v[18:21], v[220:223], v[236:239], v[50:53]
	v_mfma_f32_16x16x32_bf16 v[90:93], v[224:227], v[240:243], v[18:21]
	v_mfma_f32_16x16x32_bf16 v[18:21], v[212:215], v[244:247], v[54:57]
	v_mfma_f32_16x16x32_bf16 v[78:81], v[216:219], v[248:251], v[18:21]
	v_mfma_f32_16x16x32_bf16 v[18:21], v[220:223], v[244:247], v[58:61]
	v_mfma_f32_16x16x32_bf16 v[126:129], v[216:219], v[22:25], v[66:69]
	v_mfma_f32_16x16x32_bf16 v[74:77], v[224:227], v[248:251], v[18:21]
	s_setprio 0
	s_barrier
	s_add_i32 s3, s3, s51
	s_nop 2
	v_lshl_add_u64 v[18:19], v[184:185], 0, s[78:79]
	s_mov_b32 m0, s3
	s_add_i32 s34, s3, 0x2000
	ds_read_b128 v[42:45], v147 offset:49152
	ds_read_b128 v[46:49], v147 offset:50176
	ds_read_b128 v[228:231], v147 offset:51200
	ds_read_b128 v[232:235], v147 offset:52224
	ds_read_b128 v[236:239], v147 offset:53248
	ds_read_b128 v[240:243], v147 offset:54272
	ds_read_b128 v[244:247], v147 offset:55296
	ds_read_b128 v[248:251], v147 offset:56320
	global_load_lds_dwordx4 v[18:19], off
	v_lshl_add_u64 v[18:19], v[184:185], 0, s[82:83]
	s_mov_b32 m0, s34
	s_add_i32 s35, s35, s51
	global_load_lds_dwordx4 v[18:19], off
	v_lshl_add_u64 v[18:19], v[184:185], 0, s[84:85]
	s_mov_b32 m0, s35
	s_add_i32 s36, s35, 0x2000
	global_load_lds_dwordx4 v[18:19], off
	v_lshl_add_u64 v[18:19], v[184:185], 0, s[86:87]
	s_mov_b32 m0, s36
	s_nop 0
	global_load_lds_dwordx4 v[18:19], off
	v_lshl_add_u64 v[18:19], v[140:141], 0, s[78:79]
	s_mov_b32 m0, s57
	s_nop 0
	global_load_lds_dwordx4 v[18:19], off
	v_lshl_add_u64 v[18:19], v[140:141], 0, s[82:83]
	s_mov_b32 m0, s58
	s_nop 0
	global_load_lds_dwordx4 v[18:19], off
	s_waitcnt vmcnt(8)
	s_waitcnt lgkmcnt(0)
	s_waitcnt lgkmcnt(0)
	v_mfma_f32_16x16x32_bf16 v[18:21], v[6:9], v[42:45], v[152:155]
	v_mfma_f32_16x16x32_bf16 v[54:57], v[26:29], v[46:49], v[18:21]
	s_barrier
	s_setprio 1
	v_mfma_f32_16x16x32_bf16 v[18:21], v[30:33], v[42:45], v[156:159]
	v_mfma_f32_16x16x32_bf16 v[50:53], v[208:211], v[46:49], v[18:21]
	v_mfma_f32_16x16x32_bf16 v[18:21], v[6:9], v[228:231], v[160:163]
	v_mfma_f32_16x16x32_bf16 v[38:41], v[26:29], v[232:235], v[18:21]
	v_mfma_f32_16x16x32_bf16 v[18:21], v[30:33], v[228:231], v[164:167]
	v_mfma_f32_16x16x32_bf16 v[34:37], v[208:211], v[232:235], v[18:21]
	v_mfma_f32_16x16x32_bf16 v[18:21], v[6:9], v[236:239], v[168:171]
	v_mfma_f32_16x16x32_bf16 v[2:5], v[6:9], v[244:247], v[2:5]
	v_mfma_f32_16x16x32_bf16 v[22:25], v[26:29], v[240:243], v[18:21]
	v_mfma_f32_16x16x32_bf16 v[18:21], v[30:33], v[236:239], v[172:175]
	v_mfma_f32_16x16x32_bf16 v[6:9], v[26:29], v[248:251], v[2:5]
	v_mfma_f32_16x16x32_bf16 v[2:5], v[30:33], v[244:247], v[10:13]
	v_mfma_f32_16x16x32_bf16 v[18:21], v[208:211], v[240:243], v[18:21]
	v_mfma_f32_16x16x32_bf16 v[2:5], v[208:211], v[248:251], v[2:5]
	s_setprio 0
	s_setprio 1
	v_mfma_f32_16x16x32_bf16 v[10:13], v[212:215], v[42:45], v[14:17]
	v_mfma_f32_16x16x32_bf16 v[66:69], v[216:219], v[46:49], v[10:13]
	v_mfma_f32_16x16x32_bf16 v[10:13], v[220:223], v[42:45], v[176:179]
	v_mfma_f32_16x16x32_bf16 v[58:61], v[224:227], v[46:49], v[10:13]
	v_mfma_f32_16x16x32_bf16 v[10:13], v[212:215], v[228:231], v[180:183]
	v_mfma_f32_16x16x32_bf16 v[46:49], v[216:219], v[232:235], v[10:13]
	v_mfma_f32_16x16x32_bf16 v[10:13], v[220:223], v[228:231], v[188:191]
	v_mfma_f32_16x16x32_bf16 v[42:45], v[224:227], v[232:235], v[10:13]
	v_mfma_f32_16x16x32_bf16 v[10:13], v[212:215], v[236:239], v[192:195]
	v_mfma_f32_16x16x32_bf16 v[30:33], v[216:219], v[240:243], v[10:13]
	v_mfma_f32_16x16x32_bf16 v[10:13], v[220:223], v[236:239], v[196:199]
	v_mfma_f32_16x16x32_bf16 v[26:29], v[224:227], v[240:243], v[10:13]
	v_mfma_f32_16x16x32_bf16 v[10:13], v[212:215], v[244:247], v[200:203]
	v_mfma_f32_16x16x32_bf16 v[14:17], v[216:219], v[248:251], v[10:13]
	v_mfma_f32_16x16x32_bf16 v[10:13], v[220:223], v[244:247], v[204:207]
	v_mfma_f32_16x16x32_bf16 v[10:13], v[224:227], v[248:251], v[10:13]
	s_setprio 0
	s_barrier
	v_lshl_add_u64 v[140:141], s[24:25], 0, v[134:135]
	s_mov_b32 s37, 0
	s_mov_b64 s[6:7], 0

.LBB0_208:
	s_add_u32 s4, s46, 0xfffffe00
	s_addc_u32 s5, s47, -1
	s_add_i32 s2, s76, s3
	v_lshl_add_u32 v140, v141, 4, s2
	ds_read_b128 v[152:155], v140
	ds_read_b128 v[156:159], v140 offset:256
	ds_read_b128 v[160:163], v140 offset:512
	ds_read_b128 v[164:167], v140 offset:768
	s_waitcnt lgkmcnt(0)
	s_waitcnt lgkmcnt(0)
	v_mov_b32_e32 v168, v153
	v_mov_b32_e32 v169, v154
	v_mov_b32_e32 v153, v155
	v_pk_add_f32 v[152:153], v[168:169], v[152:153]
	s_lshl_b32 s2, s10, 8
	v_add_f32_e32 v149, v152, v153
	v_mov_b32_e32 v152, v157
	v_mov_b32_e32 v153, v158
	v_mov_b32_e32 v157, v159
	v_fmamk_f32 v149, v149, 0x3a800000, v148
	v_pk_add_f32 v[152:153], v[152:153], v[156:157]
	v_rsq_f32_e32 v170, v149
	v_add_f32_e32 v149, v152, v153
	v_mov_b32_e32 v152, v161
	v_mov_b32_e32 v153, v162
	v_mov_b32_e32 v161, v163
	v_fmamk_f32 v149, v149, 0x3a800000, v148
	v_pk_add_f32 v[152:153], v[152:153], v[160:161]
	v_rsq_f32_e32 v171, v149
	v_add_f32_e32 v149, v152, v153
	v_mov_b32_e32 v152, v165
	v_mov_b32_e32 v153, v166
	v_mov_b32_e32 v165, v167
	v_fmamk_f32 v149, v149, 0x3a800000, v148
	v_pk_add_f32 v[152:153], v[152:153], v[164:165]
	v_rsq_f32_e32 v172, v149
	v_add_f32_e32 v149, v152, v153
	ds_read_b128 v[152:155], v140 offset:2048
	ds_read_b128 v[156:159], v140 offset:2304
	ds_read_b128 v[160:163], v140 offset:2560
	ds_read_b128 v[164:167], v140 offset:2816
	v_fmamk_f32 v149, v149, 0x3a800000, v148
	s_waitcnt lgkmcnt(0)
	v_mov_b32_e32 v168, v153
	v_mov_b32_e32 v169, v154
	v_mov_b32_e32 v153, v155
	v_pk_add_f32 v[152:153], v[168:169], v[152:153]
	v_rsq_f32_e32 v173, v149
	v_add_f32_e32 v140, v152, v153
	v_mov_b32_e32 v152, v157
	v_mov_b32_e32 v153, v158
	v_mov_b32_e32 v157, v159
	v_fmamk_f32 v140, v140, 0x3a800000, v148
	v_pk_add_f32 v[152:153], v[152:153], v[156:157]
	v_rsq_f32_e32 v168, v140
	v_add_f32_e32 v140, v152, v153
	v_mov_b32_e32 v152, v161
	v_mov_b32_e32 v153, v162
	v_mov_b32_e32 v161, v163
	v_fmamk_f32 v140, v140, 0x3a800000, v148
	v_pk_add_f32 v[152:153], v[152:153], v[160:161]
	v_rsq_f32_e32 v169, v140
	v_add_f32_e32 v140, v152, v153
	v_mov_b32_e32 v152, v165
	v_mov_b32_e32 v153, v166
	v_mov_b32_e32 v165, v167
	v_fmamk_f32 v140, v140, 0x3a800000, v148
	v_pk_add_f32 v[152:153], v[152:153], v[164:165]
	v_rsq_f32_e32 v149, v140
	v_add_f32_e32 v140, v152, v153
	v_mul_f32_e32 v153, 0xbfb8aa3b, v170
	v_mul_f32_e32 v156, v119, v153
	v_exp_f32_e32 v157, v156
	v_mul_f32_e32 v156, v115, v153
	v_mul_f32_e32 v155, v114, v153
	v_exp_f32_e32 v158, v156
	v_mul_f32_e32 v156, v120, v153
	v_exp_f32_e32 v155, v155
	v_exp_f32_e32 v159, v156
	v_mul_f32_e32 v156, v116, v153
	v_mul_f32_e32 v154, v118, v153
	v_exp_f32_e32 v160, v156
	v_mul_f32_e32 v156, v121, v153
	v_exp_f32_e32 v154, v154
	v_exp_f32_e32 v161, v156
	v_mul_f32_e32 v153, v117, v153
	v_exp_f32_e32 v153, v153
	v_add_f32_e32 v155, 1.0, v155
	v_rcp_f32_e32 v156, v155
	v_add_f32_e32 v155, 1.0, v157
	v_add_f32_e32 v157, 1.0, v158
	v_add_f32_e32 v158, 1.0, v159
	v_add_f32_e32 v159, 1.0, v160
	v_add_f32_e32 v154, 1.0, v154
	v_rcp_f32_e32 v160, v159
	v_add_f32_e32 v159, 1.0, v161
	v_rcp_f32_e32 v154, v154
	v_rcp_f32_e32 v155, v155
	v_rcp_f32_e32 v157, v157
	v_rcp_f32_e32 v158, v158
	v_rcp_f32_e32 v159, v159
	v_add_f32_e32 v153, 1.0, v153
	s_add_i32 s2, s2, s59
	v_rcp_f32_e32 v161, v153
	v_add_u32_e32 v141, s2, v141
	s_lshl_b32 s2, s60, 7
	s_or_b32 s2, s2, s61
	v_mul_f32_e32 v152, v170, v170
	v_lshl_add_u32 v150, v150, 3, s2
	v_pk_mul_f32 v[120:121], v[120:121], v[128:129]
	v_pk_mul_f32 v[118:119], v[118:119], v[126:127]
	v_pk_mul_f32 v[126:127], v[152:153], v[154:155] op_sel_hi:[0,1]
	v_pk_mul_f32 v[128:129], v[152:153], v[158:159] op_sel_hi:[0,1]
	v_pk_mul_f32 v[114:115], v[114:115], v[122:123]
	v_pk_mul_f32 v[122:123], v[152:153], v[156:157] op_sel_hi:[0,1]
	v_readlane_b32 s2, v255, 0
	v_pk_mul_f32 v[120:121], v[120:121], v[128:129]
	v_pk_mul_f32 v[118:119], v[118:119], v[126:127]
	v_pk_mul_f32 v[116:117], v[116:117], v[124:125]
	v_pk_mul_f32 v[124:125], v[152:153], v[160:161] op_sel_hi:[0,1]
	v_pk_mul_f32 v[114:115], v[114:115], v[122:123]
	v_readlane_b32 s3, v255, 1
	s_waitcnt lgkmcnt(0)
	ds_read_b128 v[216:219], v145
	ds_read_b128 v[220:223], v145 offset:1024
	ds_read_b128 v[228:231], v145 offset:2048
	ds_read_b128 v[232:235], v145 offset:3072
	ds_read_b128 v[236:239], v146
	ds_read_b128 v[240:243], v146 offset:1024
	ds_read_b128 v[244:247], v146 offset:2048
	ds_read_b128 v[248:251], v146 offset:3072
	ds_read_b128 v[180:183], v147
	ds_read_b128 v[188:191], v147 offset:1024
	ds_read_b128 v[192:195], v147 offset:2048
	ds_read_b128 v[196:199], v147 offset:3072
	ds_read_b128 v[200:203], v147 offset:4096
	ds_read_b128 v[204:207], v147 offset:5120
	ds_read_b128 v[208:211], v147 offset:6144
	ds_read_b128 v[212:215], v147 offset:7168
	v_ashrrev_i32_e32 v151, 31, v150
	v_pk_mul_f32 v[116:117], v[116:117], v[124:125]
	v_cvt_pk_bf16_f32 v118, v118, v119
	v_cvt_pk_bf16_f32 v119, v120, v121
	v_cvt_pk_bf16_f32 v120, v114, v115
	v_mov_b64_e32 v[114:115], s[2:3]
	v_cvt_pk_bf16_f32 v121, v116, v117
	v_mad_i64_i32 v[122:123], s[2:3], v141, s50, v[114:115]
	v_lshlrev_b64 v[116:117], 1, v[150:151]
	v_lshl_add_u64 v[122:123], v[122:123], 0, v[116:117]
	s_cmp_eq_u32 s98, 1
	s_cbranch_scc1 .Lwt_0
	global_store_dwordx4 v[122:123], v[118:121], off
	s_branch .Lwtd_0

.LBB0_1710:
	v_bfe_u32 v143, v0, 4, 2
	s_sext_i32_i16 s83, s0
	v_lshlrev_b32_e32 v10, 4, v143
	v_lshlrev_b32_e32 v11, 6, v0
	s_movk_i32 s0, 0x3c0
	v_lshlrev_b32_e32 v13, 2, v1
	v_and_or_b32 v11, v11, s0, v10
	v_lshl_or_b32 v10, v1, 6, v10
	s_lshl_b32 s0, s3, 13
	v_and_b32_e32 v13, 32, v13
	v_bitop3_b32 v13, v10, s0, v13 bitop3:0xde
	s_lshl_b32 s0, s4, 5
	v_lshlrev_b32_e32 v12, 2, v0
	s_and_b32 s84, s0, 0x60
	v_and_b32_e32 v12, 32, v12
	s_lshl_b32 s0, s84, 7
	s_mov_b64 s[30:31], 0x80
	v_bitop3_b32 v144, s0, v11, v12 bitop3:0xf6
	v_lshl_add_u64 v[10:11], v[2:3], 0, s[30:31]
	s_add_i32 m0, s11, 0x18000
	s_mov_b64 s[34:35], 0x20080
	s_waitcnt vmcnt(2)
	s_barrier
	global_load_lds_dwordx4 v[10:11], off
	v_lshl_add_u64 v[10:11], v[2:3], 0, s[34:35]
	s_add_i32 m0, s11, 0x1a000
	s_add_i32 s86, s11, 0x8000
	global_load_lds_dwordx4 v[10:11], off
	v_lshl_add_u64 v[10:11], v[4:5], 0, s[30:31]
	s_mov_b32 m0, s86
	s_add_i32 s87, s11, 0xa000
	global_load_lds_dwordx4 v[10:11], off
	v_lshl_add_u64 v[4:5], v[4:5], 0, s[34:35]
	s_mov_b32 m0, s87
	s_mov_b64 s[38:39], 0x40080
	global_load_lds_dwordx4 v[4:5], off
	v_lshl_add_u64 v[4:5], v[2:3], 0, s[38:39]
	s_add_i32 m0, s11, 0x1c000
	s_mov_b64 s[40:41], 0x60080
	global_load_lds_dwordx4 v[4:5], off
	v_lshl_add_u64 v[2:3], v[2:3], 0, s[40:41]
	s_add_i32 m0, s11, 0x1e000
	s_lshl_b32 s82, s3, 6
	global_load_lds_dwordx4 v[2:3], off
	s_mov_b32 s0, 0x18000
	s_cmpk_lt_u32 s1, 0x100
	v_lshlrev_b32_e32 v2, 8, v0
	v_lshlrev_b32_e32 v3, 11, v6
	s_waitcnt vmcnt(6)
	s_cselect_b64 s[44:45], -1, 0
	s_lshl_b32 s1, s3, 10
	v_and_or_b32 v2, v2, s0, v3
	v_add_u32_e32 v3, v7, v8
	s_add_i32 s88, s1, 0
	v_and_b32_e32 v3, 0xe0, v3
	s_add_i32 s89, 0, 0x10000
	s_add_i32 s90, 0, 0x14000
	s_mov_b32 s85, 0
	s_add_i32 s88, s88, 0x22000
	v_or3_b32 v134, v2, v3, v9
	v_mov_b32_e32 v135, v133
	v_mov_b64_e32 v[136:137], 0x5d8
	v_mov_b64_e32 v[138:139], 0x5d7
	v_add_u32_e32 v145, s89, v144
	v_add_u32_e32 v146, s90, v144
	v_add_u32_e32 v147, 0, v13
	s_mov_b64 s[46:47], 0x100
	s_mov_b64 s[48:49], 0x20100
	s_mov_b64 s[54:55], 0x40100
	s_mov_b64 s[56:57], 0x60100
	s_mov_b64 s[58:59], 0x180
	s_mov_b64 s[60:61], 0x20180
	s_mov_b64 s[62:63], 0x40180
	s_mov_b64 s[64:65], 0x60180
	v_mov_b32_e32 v148, 0x358637bd
	s_movk_i32 s91, 0x1600
	s_barrier
	ds_read_b128 v[216:219], v145
	ds_read_b128 v[220:223], v145 offset:1024
	ds_read_b128 v[228:231], v145 offset:2048
	ds_read_b128 v[232:235], v145 offset:3072
	ds_read_b128 v[236:239], v146
	ds_read_b128 v[240:243], v146 offset:1024
	ds_read_b128 v[244:247], v146 offset:2048
	ds_read_b128 v[248:251], v146 offset:3072
	ds_read_b128 v[180:183], v147
	ds_read_b128 v[188:191], v147 offset:1024
	ds_read_b128 v[192:195], v147 offset:2048
	ds_read_b128 v[196:199], v147 offset:3072
	ds_read_b128 v[200:203], v147 offset:4096
	ds_read_b128 v[204:207], v147 offset:5120
	ds_read_b128 v[208:211], v147 offset:6144
	ds_read_b128 v[212:215], v147 offset:7168
	s_branch .LBB0_1712

.LBB0_1717:
	s_add_u32 s50, s6, 0x200
	s_addc_u32 s51, s7, 0
	s_ashr_i32 s73, s72, 31
	s_lshl_b64 s[12:13], s[72:73], 19
	s_add_u32 s78, s42, s12
	s_addc_u32 s79, s43, s13
	s_and_b64 s[12:13], s[0:1], exec
	s_cselect_b32 s73, s79, s15
	s_cselect_b32 s93, s78, s14
	s_ashr_i32 s67, s66, 31
	s_lshl_b64 s[12:13], s[66:67], 19
	v_readlane_b32 s18, v255, 15
	v_readlane_b32 s19, v255, 16
	s_add_u32 s74, s18, s12
	s_addc_u32 s75, s19, s13
	s_and_b64 s[12:13], s[0:1], exec
	s_cselect_b32 s67, s75, s7
	s_cselect_b32 s94, s74, s6
	v_lshl_add_u64 v[140:141], s[14:15], 0, v[130:131]
	s_add_i32 s95, s11, 0xc000
	v_lshl_add_u64 v[66:67], v[140:141], 0, s[38:39]
	s_mov_b32 m0, s95
	s_add_i32 s96, s11, 0xe000
	global_load_lds_dwordx4 v[66:67], off
	v_lshl_add_u64 v[66:67], v[140:141], 0, s[40:41]
	s_mov_b32 m0, s96
	s_nop 0
	global_load_lds_dwordx4 v[66:67], off
	s_waitcnt vmcnt(8)
	s_waitcnt lgkmcnt(0)
	s_waitcnt lgkmcnt(0)
	v_mfma_f32_16x16x32_bf16 v[86:89], v[228:231], v[200:203], 0
	v_mfma_f32_16x16x32_bf16 v[90:93], v[232:235], v[204:207], v[86:89]
	s_barrier
	s_setprio 1
	v_mfma_f32_16x16x32_bf16 v[86:89], v[216:219], v[208:211], 0
	v_mfma_f32_16x16x32_bf16 v[66:69], v[216:219], v[180:183], 0
	v_mfma_f32_16x16x32_bf16 v[70:73], v[228:231], v[180:183], 0
	v_mfma_f32_16x16x32_bf16 v[74:77], v[216:219], v[192:195], 0
	v_mfma_f32_16x16x32_bf16 v[78:81], v[228:231], v[192:195], 0
	v_mfma_f32_16x16x32_bf16 v[82:85], v[216:219], v[200:203], 0
	v_mfma_f32_16x16x32_bf16 v[94:97], v[220:223], v[212:215], v[86:89]
	v_mfma_f32_16x16x32_bf16 v[86:89], v[228:231], v[208:211], 0
	v_mfma_f32_16x16x32_bf16 v[66:69], v[220:223], v[188:191], v[66:69]
	v_mfma_f32_16x16x32_bf16 v[70:73], v[232:235], v[188:191], v[70:73]
	v_mfma_f32_16x16x32_bf16 v[74:77], v[220:223], v[196:199], v[74:77]
	v_mfma_f32_16x16x32_bf16 v[78:81], v[232:235], v[196:199], v[78:81]
	v_mfma_f32_16x16x32_bf16 v[82:85], v[220:223], v[204:207], v[82:85]
	v_mfma_f32_16x16x32_bf16 v[106:109], v[232:235], v[212:215], v[86:89]
	s_setprio 0
	s_setprio 1
	v_mfma_f32_16x16x32_bf16 v[86:89], v[236:239], v[180:183], 0
	v_mfma_f32_16x16x32_bf16 v[34:37], v[244:247], v[180:183], 0
	v_mfma_f32_16x16x32_bf16 v[110:113], v[240:243], v[188:191], v[86:89]
	v_mfma_f32_16x16x32_bf16 v[34:37], v[248:251], v[188:191], v[34:37]
	v_mfma_f32_16x16x32_bf16 v[38:41], v[236:239], v[192:195], 0
	v_mfma_f32_16x16x32_bf16 v[42:45], v[244:247], v[192:195], 0
	v_mfma_f32_16x16x32_bf16 v[38:41], v[240:243], v[196:199], v[38:41]
	v_mfma_f32_16x16x32_bf16 v[42:45], v[248:251], v[196:199], v[42:45]
	v_mfma_f32_16x16x32_bf16 v[46:49], v[236:239], v[200:203], 0
	v_mfma_f32_16x16x32_bf16 v[50:53], v[244:247], v[200:203], 0
	v_mfma_f32_16x16x32_bf16 v[46:49], v[240:243], v[204:207], v[46:49]
	v_mfma_f32_16x16x32_bf16 v[50:53], v[248:251], v[204:207], v[50:53]
	v_mfma_f32_16x16x32_bf16 v[54:57], v[236:239], v[208:211], 0
	v_mfma_f32_16x16x32_bf16 v[58:61], v[244:247], v[208:211], 0
	v_mfma_f32_16x16x32_bf16 v[54:57], v[240:243], v[212:215], v[54:57]
	v_mfma_f32_16x16x32_bf16 v[58:61], v[248:251], v[212:215], v[58:61]
	s_setprio 0
	s_barrier
	v_lshl_add_u64 v[184:185], s[6:7], 0, v[132:133]
	s_add_i32 s97, s89, s52
	v_lshl_add_u64 v[150:151], v[184:185], 0, s[46:47]
	s_mov_b32 m0, s97
	s_add_i32 vcc_lo, s97, 0x2000
	ds_read_b128 v[62:65], v147 offset:16384
	ds_read_b128 v[86:89], v147 offset:17408
	ds_read_b128 v[98:101], v147 offset:18432
	ds_read_b128 v[102:105], v147 offset:19456
	ds_read_b128 v[114:117], v147 offset:20480
	ds_read_b128 v[118:121], v147 offset:21504
	ds_read_b128 v[122:125], v147 offset:22528
	ds_read_b128 v[126:129], v147 offset:23552
	global_load_lds_dwordx4 v[150:151], off
	v_lshl_add_u64 v[150:151], v[184:185], 0, s[48:49]
	s_mov_b32 m0, vcc_lo
	s_add_i32 s33, s90, s52
	global_load_lds_dwordx4 v[150:151], off
	v_lshl_add_u64 v[150:151], v[184:185], 0, s[54:55]
	s_mov_b32 m0, s33
	s_add_i32 vcc_hi, s33, 0x2000
	global_load_lds_dwordx4 v[150:151], off
	v_lshl_add_u64 v[150:151], v[184:185], 0, s[56:57]
	s_mov_b32 m0, vcc_hi
	s_nop 0
	global_load_lds_dwordx4 v[150:151], off
	v_lshl_add_u64 v[150:151], v[140:141], 0, s[46:47]
	s_mov_b32 m0, s11
	s_nop 0
	global_load_lds_dwordx4 v[150:151], off
	v_lshl_add_u64 v[150:151], v[140:141], 0, s[48:49]
	s_mov_b32 m0, s77
	s_nop 0
	global_load_lds_dwordx4 v[150:151], off
	s_waitcnt vmcnt(8)
	s_waitcnt lgkmcnt(0)
	s_waitcnt lgkmcnt(0)
	v_mfma_f32_16x16x32_bf16 v[150:153], v[216:219], v[62:65], 0
	v_mfma_f32_16x16x32_bf16 v[160:163], v[216:219], v[98:101], 0
	s_barrier
	s_setprio 1
	v_mfma_f32_16x16x32_bf16 v[168:171], v[216:219], v[114:117], 0
	v_mfma_f32_16x16x32_bf16 v[2:5], v[216:219], v[122:125], 0
	v_mfma_f32_16x16x32_bf16 v[152:155], v[220:223], v[86:89], v[150:153]
	v_mfma_f32_16x16x32_bf16 v[160:163], v[220:223], v[102:105], v[160:163]
	v_mfma_f32_16x16x32_bf16 v[168:171], v[220:223], v[118:121], v[168:171]
	v_mfma_f32_16x16x32_bf16 v[2:5], v[220:223], v[126:129], v[2:5]
	v_mfma_f32_16x16x32_bf16 v[6:9], v[228:231], v[122:125], 0
	v_mfma_f32_16x16x32_bf16 v[156:159], v[228:231], v[62:65], 0
	v_mfma_f32_16x16x32_bf16 v[164:167], v[228:231], v[98:101], 0
	v_mfma_f32_16x16x32_bf16 v[172:175], v[228:231], v[114:117], 0
	v_mfma_f32_16x16x32_bf16 v[10:13], v[232:235], v[126:129], v[6:9]
	v_mfma_f32_16x16x32_bf16 v[156:159], v[232:235], v[86:89], v[156:159]
	v_mfma_f32_16x16x32_bf16 v[164:167], v[232:235], v[102:105], v[164:167]
	v_mfma_f32_16x16x32_bf16 v[172:175], v[232:235], v[118:121], v[172:175]
	s_setprio 0
	s_setprio 1
	v_mfma_f32_16x16x32_bf16 v[6:9], v[236:239], v[62:65], 0
	v_mfma_f32_16x16x32_bf16 v[14:17], v[240:243], v[86:89], v[6:9]
	v_mfma_f32_16x16x32_bf16 v[6:9], v[244:247], v[62:65], 0
	v_mfma_f32_16x16x32_bf16 v[176:179], v[248:251], v[86:89], v[6:9]
	v_mfma_f32_16x16x32_bf16 v[6:9], v[236:239], v[98:101], 0
	v_mfma_f32_16x16x32_bf16 v[180:183], v[240:243], v[102:105], v[6:9]
	v_mfma_f32_16x16x32_bf16 v[6:9], v[244:247], v[98:101], 0
	v_mfma_f32_16x16x32_bf16 v[188:191], v[248:251], v[102:105], v[6:9]
	v_mfma_f32_16x16x32_bf16 v[6:9], v[236:239], v[114:117], 0
	v_mfma_f32_16x16x32_bf16 v[192:195], v[240:243], v[118:121], v[6:9]
	v_mfma_f32_16x16x32_bf16 v[6:9], v[244:247], v[114:117], 0
	v_mfma_f32_16x16x32_bf16 v[196:199], v[248:251], v[118:121], v[6:9]
	v_mfma_f32_16x16x32_bf16 v[6:9], v[236:239], v[122:125], 0
	v_mfma_f32_16x16x32_bf16 v[200:203], v[240:243], v[126:129], v[6:9]
	v_mfma_f32_16x16x32_bf16 v[6:9], v[244:247], v[122:125], 0
	v_mfma_f32_16x16x32_bf16 v[204:207], v[248:251], v[126:129], v[6:9]
	s_setprio 0
	s_barrier
	s_add_i32 s12, 0, 0x18000
	s_add_i32 s3, 0, 0x1c000
	v_add_u32_e32 v149, s12, v144
	v_add_u32_e32 v150, s3, v144
	s_nop 0
	ds_read_b128 v[6:9], v149
	ds_read_b128 v[26:29], v149 offset:1024
	ds_read_b128 v[30:33], v149 offset:2048
	ds_read_b128 v[208:211], v149 offset:3072
	ds_read_b128 v[212:215], v150
	ds_read_b128 v[216:219], v150 offset:1024
	ds_read_b128 v[220:223], v150 offset:2048
	ds_read_b128 v[224:227], v150 offset:3072
	s_mov_b32 m0, s80
	v_lshl_add_u64 v[62:63], v[140:141], 0, s[54:55]
	ds_read_b128 v[18:21], v147 offset:32768
	ds_read_b128 v[22:25], v147 offset:33792
	ds_read_b128 v[228:231], v147 offset:34816
	ds_read_b128 v[232:235], v147 offset:35840
	ds_read_b128 v[236:239], v147 offset:36864
	ds_read_b128 v[240:243], v147 offset:37888
	ds_read_b128 v[244:247], v147 offset:38912
	ds_read_b128 v[248:251], v147 offset:39936
	global_load_lds_dwordx4 v[62:63], off
	v_lshl_add_u64 v[62:63], v[140:141], 0, s[56:57]
	s_mov_b32 m0, s81
	s_nop 0
	global_load_lds_dwordx4 v[62:63], off
	s_waitcnt vmcnt(8)
	s_waitcnt lgkmcnt(0)
	s_waitcnt lgkmcnt(0)
	v_mfma_f32_16x16x32_bf16 v[62:65], v[6:9], v[18:21], v[66:69]
	v_mfma_f32_16x16x32_bf16 v[118:121], v[26:29], v[22:25], v[62:65]
	s_barrier
	s_setprio 1
	v_mfma_f32_16x16x32_bf16 v[62:65], v[30:33], v[18:21], v[70:73]
	v_mfma_f32_16x16x32_bf16 v[114:117], v[208:211], v[22:25], v[62:65]
	v_mfma_f32_16x16x32_bf16 v[62:65], v[6:9], v[228:231], v[74:77]
	v_mfma_f32_16x16x32_bf16 v[102:105], v[26:29], v[232:235], v[62:65]
	v_mfma_f32_16x16x32_bf16 v[62:65], v[30:33], v[228:231], v[78:81]
	v_mfma_f32_16x16x32_bf16 v[98:101], v[208:211], v[232:235], v[62:65]
	v_mfma_f32_16x16x32_bf16 v[62:65], v[6:9], v[236:239], v[82:85]
	v_mfma_f32_16x16x32_bf16 v[86:89], v[26:29], v[240:243], v[62:65]
	v_mfma_f32_16x16x32_bf16 v[62:65], v[30:33], v[236:239], v[90:93]
	v_mfma_f32_16x16x32_bf16 v[82:85], v[208:211], v[240:243], v[62:65]
	v_mfma_f32_16x16x32_bf16 v[62:65], v[6:9], v[244:247], v[94:97]
	v_mfma_f32_16x16x32_bf16 v[70:73], v[26:29], v[248:251], v[62:65]
	v_mfma_f32_16x16x32_bf16 v[62:65], v[30:33], v[244:247], v[106:109]
	v_mfma_f32_16x16x32_bf16 v[62:65], v[208:211], v[248:251], v[62:65]
	s_setprio 0
	s_setprio 1
	v_mfma_f32_16x16x32_bf16 v[66:69], v[212:215], v[18:21], v[110:113]
	v_mfma_f32_16x16x32_bf16 v[18:21], v[220:223], v[18:21], v[34:37]
	v_mfma_f32_16x16x32_bf16 v[122:125], v[224:227], v[22:25], v[18:21]
	v_mfma_f32_16x16x32_bf16 v[18:21], v[212:215], v[228:231], v[38:41]
	v_mfma_f32_16x16x32_bf16 v[110:113], v[216:219], v[232:235], v[18:21]
	v_mfma_f32_16x16x32_bf16 v[18:21], v[220:223], v[228:231], v[42:45]
	v_mfma_f32_16x16x32_bf16 v[106:109], v[224:227], v[232:235], v[18:21]
	v_mfma_f32_16x16x32_bf16 v[18:21], v[212:215], v[236:239], v[46:49]
	v_mfma_f32_16x16x32_bf16 v[94:97], v[216:219], v[240:243], v[18:21]
	v_mfma_f32_16x16x32_bf16 v[18:21], v[220:223], v[236:239], v[50:53]
	v_mfma_f32_16x16x32_bf16 v[90:93], v[224:227], v[240:243], v[18:21]
	v_mfma_f32_16x16x32_bf16 v[18:21], v[212:215], v[244:247], v[54:57]
	v_mfma_f32_16x16x32_bf16 v[78:81], v[216:219], v[248:251], v[18:21]
	v_mfma_f32_16x16x32_bf16 v[18:21], v[220:223], v[244:247], v[58:61]
	v_mfma_f32_16x16x32_bf16 v[126:129], v[216:219], v[22:25], v[66:69]
	v_mfma_f32_16x16x32_bf16 v[74:77], v[224:227], v[248:251], v[18:21]
	s_setprio 0
	s_barrier
	s_add_i32 s12, s12, s52
	s_nop 2
	v_lshl_add_u64 v[18:19], v[184:185], 0, s[58:59]
	s_mov_b32 m0, s12
	s_add_i32 s13, s12, 0x2000
	ds_read_b128 v[42:45], v147 offset:49152
	ds_read_b128 v[46:49], v147 offset:50176
	ds_read_b128 v[228:231], v147 offset:51200
	ds_read_b128 v[232:235], v147 offset:52224
	ds_read_b128 v[236:239], v147 offset:53248
	ds_read_b128 v[240:243], v147 offset:54272
	ds_read_b128 v[244:247], v147 offset:55296
	ds_read_b128 v[248:251], v147 offset:56320
	global_load_lds_dwordx4 v[18:19], off
	v_lshl_add_u64 v[18:19], v[184:185], 0, s[60:61]
	s_mov_b32 m0, s13
	s_add_i32 s3, s3, s52
	global_load_lds_dwordx4 v[18:19], off
	v_lshl_add_u64 v[18:19], v[184:185], 0, s[62:63]
	s_mov_b32 m0, s3
	s_add_i32 s36, s3, 0x2000
	global_load_lds_dwordx4 v[18:19], off
	v_lshl_add_u64 v[18:19], v[184:185], 0, s[64:65]
	s_mov_b32 m0, s36
	s_nop 0
	global_load_lds_dwordx4 v[18:19], off
	v_lshl_add_u64 v[18:19], v[140:141], 0, s[58:59]
	s_mov_b32 m0, s86
	s_nop 0
	global_load_lds_dwordx4 v[18:19], off
	v_lshl_add_u64 v[18:19], v[140:141], 0, s[60:61]
	s_mov_b32 m0, s87
	s_nop 0
	global_load_lds_dwordx4 v[18:19], off
	s_waitcnt vmcnt(8)
	s_waitcnt lgkmcnt(0)
	s_waitcnt lgkmcnt(0)
	v_mfma_f32_16x16x32_bf16 v[18:21], v[6:9], v[42:45], v[152:155]
	v_mfma_f32_16x16x32_bf16 v[54:57], v[26:29], v[46:49], v[18:21]
	s_barrier
	s_setprio 1
	v_mfma_f32_16x16x32_bf16 v[18:21], v[30:33], v[42:45], v[156:159]
	v_mfma_f32_16x16x32_bf16 v[50:53], v[208:211], v[46:49], v[18:21]
	v_mfma_f32_16x16x32_bf16 v[18:21], v[6:9], v[228:231], v[160:163]
	v_mfma_f32_16x16x32_bf16 v[38:41], v[26:29], v[232:235], v[18:21]
	v_mfma_f32_16x16x32_bf16 v[18:21], v[30:33], v[228:231], v[164:167]
	v_mfma_f32_16x16x32_bf16 v[34:37], v[208:211], v[232:235], v[18:21]
	v_mfma_f32_16x16x32_bf16 v[18:21], v[6:9], v[236:239], v[168:171]
	v_mfma_f32_16x16x32_bf16 v[2:5], v[6:9], v[244:247], v[2:5]
	v_mfma_f32_16x16x32_bf16 v[22:25], v[26:29], v[240:243], v[18:21]
	v_mfma_f32_16x16x32_bf16 v[18:21], v[30:33], v[236:239], v[172:175]
	v_mfma_f32_16x16x32_bf16 v[6:9], v[26:29], v[248:251], v[2:5]
	v_mfma_f32_16x16x32_bf16 v[2:5], v[30:33], v[244:247], v[10:13]
	v_mfma_f32_16x16x32_bf16 v[18:21], v[208:211], v[240:243], v[18:21]
	v_mfma_f32_16x16x32_bf16 v[2:5], v[208:211], v[248:251], v[2:5]
	s_setprio 0
	s_setprio 1
	v_mfma_f32_16x16x32_bf16 v[10:13], v[212:215], v[42:45], v[14:17]
	v_mfma_f32_16x16x32_bf16 v[66:69], v[216:219], v[46:49], v[10:13]
	v_mfma_f32_16x16x32_bf16 v[10:13], v[220:223], v[42:45], v[176:179]
	v_mfma_f32_16x16x32_bf16 v[58:61], v[224:227], v[46:49], v[10:13]
	v_mfma_f32_16x16x32_bf16 v[10:13], v[212:215], v[228:231], v[180:183]
	v_mfma_f32_16x16x32_bf16 v[46:49], v[216:219], v[232:235], v[10:13]
	v_mfma_f32_16x16x32_bf16 v[10:13], v[220:223], v[228:231], v[188:191]
	v_mfma_f32_16x16x32_bf16 v[42:45], v[224:227], v[232:235], v[10:13]
	v_mfma_f32_16x16x32_bf16 v[10:13], v[212:215], v[236:239], v[192:195]
	v_mfma_f32_16x16x32_bf16 v[30:33], v[216:219], v[240:243], v[10:13]
	v_mfma_f32_16x16x32_bf16 v[10:13], v[220:223], v[236:239], v[196:199]
	v_mfma_f32_16x16x32_bf16 v[26:29], v[224:227], v[240:243], v[10:13]
	v_mfma_f32_16x16x32_bf16 v[10:13], v[212:215], v[244:247], v[200:203]
	v_mfma_f32_16x16x32_bf16 v[14:17], v[216:219], v[248:251], v[10:13]
	v_mfma_f32_16x16x32_bf16 v[10:13], v[220:223], v[244:247], v[204:207]
	v_mfma_f32_16x16x32_bf16 v[10:13], v[224:227], v[248:251], v[10:13]
	s_setprio 0
	s_barrier
	v_lshl_add_u64 v[140:141], s[14:15], 0, v[134:135]
	s_mov_b32 s37, 0
	s_mov_b64 s[6:7], 0

.LBB0_1725:
	s_add_u32 s4, s50, 0xfffffe00
	s_addc_u32 s5, s51, -1
	s_add_i32 s3, s88, s12
	v_lshl_add_u32 v140, v141, 4, s3
	ds_read_b128 v[152:155], v140
	ds_read_b128 v[156:159], v140 offset:256
	ds_read_b128 v[160:163], v140 offset:512
	ds_read_b128 v[164:167], v140 offset:768
	s_waitcnt lgkmcnt(0)
	s_waitcnt lgkmcnt(0)
	v_mov_b32_e32 v168, v153
	v_mov_b32_e32 v169, v154
	v_mov_b32_e32 v153, v155
	v_pk_add_f32 v[152:153], v[168:169], v[152:153]
	s_lshl_b32 s3, s10, 8
	v_add_f32_e32 v149, v152, v153
	v_mov_b32_e32 v152, v157
	v_mov_b32_e32 v153, v158
	v_mov_b32_e32 v157, v159
	v_fmamk_f32 v149, v149, 0x3a800000, v148
	v_pk_add_f32 v[152:153], v[152:153], v[156:157]
	v_rsq_f32_e32 v170, v149
	v_add_f32_e32 v149, v152, v153
	v_mov_b32_e32 v152, v161
	v_mov_b32_e32 v153, v162
	v_mov_b32_e32 v161, v163
	v_fmamk_f32 v149, v149, 0x3a800000, v148
	v_pk_add_f32 v[152:153], v[152:153], v[160:161]
	v_rsq_f32_e32 v171, v149
	v_add_f32_e32 v149, v152, v153
	v_mov_b32_e32 v152, v165
	v_mov_b32_e32 v153, v166
	v_mov_b32_e32 v165, v167
	v_fmamk_f32 v149, v149, 0x3a800000, v148
	v_pk_add_f32 v[152:153], v[152:153], v[164:165]
	v_rsq_f32_e32 v172, v149
	v_add_f32_e32 v149, v152, v153
	ds_read_b128 v[152:155], v140 offset:2048
	ds_read_b128 v[156:159], v140 offset:2304
	ds_read_b128 v[160:163], v140 offset:2560
	ds_read_b128 v[164:167], v140 offset:2816
	v_fmamk_f32 v149, v149, 0x3a800000, v148
	s_waitcnt lgkmcnt(0)
	v_mov_b32_e32 v168, v153
	v_mov_b32_e32 v169, v154
	v_mov_b32_e32 v153, v155
	v_pk_add_f32 v[152:153], v[168:169], v[152:153]
	v_rsq_f32_e32 v173, v149
	v_add_f32_e32 v140, v152, v153
	v_mov_b32_e32 v152, v157
	v_mov_b32_e32 v153, v158
	v_mov_b32_e32 v157, v159
	v_fmamk_f32 v140, v140, 0x3a800000, v148
	v_pk_add_f32 v[152:153], v[152:153], v[156:157]
	v_rsq_f32_e32 v168, v140
	v_add_f32_e32 v140, v152, v153
	v_mov_b32_e32 v152, v161
	v_mov_b32_e32 v153, v162
	v_mov_b32_e32 v161, v163
	v_fmamk_f32 v140, v140, 0x3a800000, v148
	v_pk_add_f32 v[152:153], v[152:153], v[160:161]
	v_rsq_f32_e32 v169, v140
	v_add_f32_e32 v140, v152, v153
	v_mov_b32_e32 v152, v165
	v_mov_b32_e32 v153, v166
	v_mov_b32_e32 v165, v167
	v_fmamk_f32 v140, v140, 0x3a800000, v148
	v_pk_add_f32 v[152:153], v[152:153], v[164:165]
	v_rsq_f32_e32 v149, v140
	v_add_f32_e32 v140, v152, v153
	v_mul_f32_e32 v153, 0xbfb8aa3b, v170
	v_mul_f32_e32 v156, v119, v153
	v_exp_f32_e32 v157, v156
	v_mul_f32_e32 v156, v115, v153
	v_mul_f32_e32 v155, v114, v153
	v_exp_f32_e32 v158, v156
	v_mul_f32_e32 v156, v120, v153
	v_exp_f32_e32 v155, v155
	v_exp_f32_e32 v159, v156
	v_mul_f32_e32 v156, v116, v153
	v_mul_f32_e32 v154, v118, v153
	v_exp_f32_e32 v160, v156
	v_mul_f32_e32 v156, v121, v153
	v_exp_f32_e32 v154, v154
	v_exp_f32_e32 v161, v156
	v_mul_f32_e32 v153, v117, v153
	v_exp_f32_e32 v153, v153
	v_add_f32_e32 v155, 1.0, v155
	v_rcp_f32_e32 v156, v155
	v_add_f32_e32 v155, 1.0, v157
	v_add_f32_e32 v157, 1.0, v158
	v_add_f32_e32 v158, 1.0, v159
	v_add_f32_e32 v159, 1.0, v160
	v_add_f32_e32 v154, 1.0, v154
	v_rcp_f32_e32 v160, v159
	v_add_f32_e32 v159, 1.0, v161
	v_rcp_f32_e32 v154, v154
	v_rcp_f32_e32 v155, v155
	v_rcp_f32_e32 v157, v157
	v_rcp_f32_e32 v158, v158
	v_rcp_f32_e32 v159, v159
	v_add_f32_e32 v153, 1.0, v153
	v_rcp_f32_e32 v161, v153
	s_add_i32 s3, s3, s82
	v_add_u32_e32 v141, s3, v141
	s_lshl_b32 s3, s83, 7
	v_mul_f32_e32 v152, v170, v170
	s_or_b32 s3, s3, s84
	v_pk_mul_f32 v[120:121], v[120:121], v[128:129]
	v_pk_mul_f32 v[118:119], v[118:119], v[126:127]
	v_pk_mul_f32 v[126:127], v[152:153], v[154:155] op_sel_hi:[0,1]
	v_pk_mul_f32 v[128:129], v[152:153], v[158:159] op_sel_hi:[0,1]
	v_pk_mul_f32 v[114:115], v[114:115], v[122:123]
	v_pk_mul_f32 v[122:123], v[152:153], v[156:157] op_sel_hi:[0,1]
	v_readlane_b32 s12, v255, 0
	v_lshl_add_u32 v150, v150, 3, s3
	v_pk_mul_f32 v[120:121], v[120:121], v[128:129]
	v_pk_mul_f32 v[118:119], v[118:119], v[126:127]
	v_pk_mul_f32 v[116:117], v[116:117], v[124:125]
	v_pk_mul_f32 v[124:125], v[152:153], v[160:161] op_sel_hi:[0,1]
	v_pk_mul_f32 v[114:115], v[114:115], v[122:123]
	v_readlane_b32 s13, v255, 1
	s_waitcnt lgkmcnt(0)
	ds_read_b128 v[216:219], v145
	ds_read_b128 v[220:223], v145 offset:1024
	ds_read_b128 v[228:231], v145 offset:2048
	ds_read_b128 v[232:235], v145 offset:3072
	ds_read_b128 v[236:239], v146
	ds_read_b128 v[240:243], v146 offset:1024
	ds_read_b128 v[244:247], v146 offset:2048
	ds_read_b128 v[248:251], v146 offset:3072
	ds_read_b128 v[180:183], v147
	ds_read_b128 v[188:191], v147 offset:1024
	ds_read_b128 v[192:195], v147 offset:2048
	ds_read_b128 v[196:199], v147 offset:3072
	ds_read_b128 v[200:203], v147 offset:4096
	ds_read_b128 v[204:207], v147 offset:5120
	ds_read_b128 v[208:211], v147 offset:6144
	ds_read_b128 v[212:215], v147 offset:7168
	v_ashrrev_i32_e32 v151, 31, v150
	v_pk_mul_f32 v[116:117], v[116:117], v[124:125]
	v_cvt_pk_bf16_f32 v118, v118, v119
	v_cvt_pk_bf16_f32 v119, v120, v121
	v_cvt_pk_bf16_f32 v120, v114, v115
	v_mov_b64_e32 v[114:115], s[12:13]
	v_cvt_pk_bf16_f32 v121, v116, v117
	v_mad_i64_i32 v[122:123], s[12:13], v141, s91, v[114:115]
	v_lshlrev_b64 v[116:117], 1, v[150:151]
	v_lshl_add_u64 v[122:123], v[122:123], 0, v[116:117]
	s_cmp_eq_u32 s98, 1
	s_cbranch_scc1 .Lwt_8
	global_store_dwordx4 v[122:123], v[118:121], off
	s_branch .Lwtd_8
